# attention: first PV group transpose-reads issued early (hide LDS latency); K swizzle conflict-free; K/V loads global; no barrier after slot 5
# speedup vs baseline: 1.0109x; 1.0086x over previous
; __device__ __forceinline__ int v_st(int k, int c) { const int kk = (k & ~0xC) | ((k & 4) << 1) | ((k & 8) >> 1); return ((kk >> 3) * 4 + (c >> 5)) * 512 + ((kk & 7) * 32 + (c & 31)) * 2; }
; __device__ __forceinline__ int v_rd_base(int lane) { return ((lane & 3) << 3) | (((lane >> 2) & 3) << 6) | (((lane >> 4) & 1) << 5) | (((lane >> 5) & 1) << 8); }
; #define SWRITE(b, i) do { *(bf16x8*)((char*)V_lds + (b) * SHM_V + vst0) = sr_[i].vs0;          \
;     *(bf16x8*)((char*)V_lds + (b) * SHM_V + vst1) = sr_[i].vs1; int kc = sc * 2;               \
;     *(bf16x8*)((char*)K_lds + (b) * SHM_K + KSWZ(sr, kc)) = sr_[i].ks0;                       \
;     *(bf16x8*)((char*)K_lds + (b) * SHM_K + KSWZ(32 + sr, kc)) = sr_[i].ks1; } while (0)
; __device__ __forceinline__ void attn_body(const bf16_t* __restrict__ Qb, const bf16_t* __restrict__ Kh, const bf16_t* __restrict__ Vh,
;                                           bf16_t* __restrict__ Ob, const bf16_t* __restrict__ AGb, int seq, char* lds) {
;     ...
;   const bf16_t* Qw = Qb + (long)(wid * QBLK + r32) * LDQ + hi * 8;
; #pragma unroll
;   for (int d0 = 0; d0 < 8; ++d0) qr[d0] = *reinterpret_cast<const bf16x8*>(Qw + d0 * 16);
;   const int sr = tid >> 4, sc = (tid & 15) * 8, vst0 = v_st(sr, sc), vst1 = v_st(32 + sr, sc);
;   const int vb0 = (int)(uintptr_t)V_lds + v_rd_base(lane);
;   const unsigned goff0 = (unsigned)(sr * LDK + sc) * 2u, goff1 = (unsigned)((32 + sr) * LDK + sc) * 2u;
;   struct { bf16x8 vs0, vs1, ks0, ks1; } sr_[2];
;     ...
;   f32x16 pA0, pA1, pB0, pB1; float mnA, mnB, alA, alB; bf16x8 pa0, pa1, pa2, pa3; const int NT = seq / KVBLK;
;   constexpr int SE = 0, SO = 1;
;   SLOAD(SE, 0); asm volatile("s_waitcnt vmcnt(0)" ::: "memory"); SWRITE(0, SE); __syncthreads();
;   qkt(pA0, pA1, K_lds, qr, r32, hi); partialSM(pA0, pA1, m_reg, mnA, alA);
.LBB0_198:
	s_lshr_b32 s23, s3, 2
	s_mul_i32 s1, s18, 0x8800
	s_mul_hi_i32 s0, s18, 0x8800
	s_add_u32 s26, s8, s1
	s_addc_u32 s27, s9, s0
	s_lshl_b32 s28, s3, 7
	s_lshl_b32 s0, s3, 8
	s_add_u32 s20, s26, s0
	s_addc_u32 s21, s27, 0
	s_mul_hi_u32 s22, s23, 0x210000
	s_mul_i32 s23, s23, 0x210000
	v_mov_b32_e32 v64, v190
	s_add_u32 s4, s12, s23
	s_addc_u32 s5, s13, s22
	v_ashrrev_i32_e32 v18, 4, v64
	v_lshlrev_b32_e32 v19, 3, v64
	v_and_b32_e32 v0, 0x78, v19
	v_add_u32_e32 v21, 32, v18
	s_add_u32 s0, s10, s23
	v_lshlrev_b32_e32 v20, 1, v0
	v_lshlrev_b32_e32 v22, 8, v18
	v_lshlrev_b32_e32 v23, 8, v21
	s_addc_u32 s1, s11, s22
	v_or_b32_e32 v96, v20, v22
	v_or_b32_e32 v184, v23, v20
	v_mov_b32_e32 v185, v97
	v_lshl_add_u64 v[0:1], s[0:1], 0, v[96:97]
	v_lshl_add_u64 v[4:5], s[0:1], 0, v[184:185]
	v_lshl_add_u64 v[8:9], s[4:5], 0, v[96:97]
	v_lshl_add_u64 v[12:13], s[4:5], 0, v[184:185]
	global_load_dwordx4 v[0:3], v[0:1], off
	s_nop 0
	global_load_dwordx4 v[4:7], v[4:5], off
	s_nop 0
	global_load_dwordx4 v[8:11], v[8:9], off
	s_nop 0
	global_load_dwordx4 v[12:15], v[12:13], off
	v_ashrrev_i32_e32 v48, 1, v64
	s_movk_i32 s3, 0xffe0
	v_bfe_u32 v197, v64, 5, 1
	v_bfi_b32 v24, s3, v48, v64
	v_mov_b64_e32 v[16:17], s[20:21]
	v_mad_i64_i32 v[16:17], s[20:21], v24, s33, v[16:17]
	v_lshlrev_b32_e32 v180, 4, v197
	v_mov_b32_e32 v181, v97
	v_lshl_add_u64 v[16:17], v[16:17], 0, v[180:181]
	global_load_dwordx4 v[118:121], v[16:17], off
	global_load_dwordx4 v[114:117], v[16:17], off offset:32
	global_load_dwordx4 v[126:129], v[16:17], off offset:64
	global_load_dwordx4 v[122:125], v[16:17], off offset:96
	global_load_dwordx4 v[110:113], v[16:17], off offset:128
	global_load_dwordx4 v[106:109], v[16:17], off offset:160
	global_load_dwordx4 v[102:105], v[16:17], off offset:192
	global_load_dwordx4 v[98:101], v[16:17], off offset:224
	v_and_b32_e32 v25, 0xfffff0, v18
	v_lshlrev_b32_e32 v26, 1, v18
	v_and_or_b32 v25, v26, 8, v25
	v_and_b32_e32 v26, 0xfffff0, v21
	v_lshlrev_b32_e32 v21, 1, v21
	v_and_b32_e32 v24, 0x70, v64
	v_bfe_u32 v67, v64, 8, 1
	v_lshl_or_b32 v24, v67, 7, v24
	v_lshrrev_b32_e32 v27, 1, v18
	v_bfe_u32 v19, v19, 5, 2
	v_and_b32_e32 v18, 3, v18
	v_lshrrev_b32_e32 v25, 1, v25
	v_and_or_b32 v21, v21, 8, v26
	v_and_or_b32 v18, v27, 4, v18
	v_and_b32_e32 v27, 48, v20
	v_bitop3_b32 v22, v20, v22, v24 bitop3:0xde
	v_bitop3_b32 v20, v20, v23, v24 bitop3:0xde
	v_or_b32_e32 v23, v25, v19
	v_lshrrev_b32_e32 v21, 1, v21
	v_lshlrev_b32_e32 v18, 6, v18
	v_add_u32_e32 v203, 0, v20
	v_lshlrev_b32_e32 v20, 9, v23
	v_or_b32_e32 v19, v21, v19
	v_and_b32_e32 v198, 31, v64
	v_lshlrev_b32_e32 v49, 4, v64
	v_or3_b32 v16, v20, v18, v27
	v_lshlrev_b32_e32 v17, 9, v19
	v_lshlrev_b32_e32 v65, 8, v198
	v_and_b32_e32 v66, 0x70, v49
	v_bfe_u32 v67, v64, 4, 1
	v_lshl_or_b32 v66, v67, 7, v66
	v_or3_b32 v17, v17, v18, v27
	v_add_u32_e32 v204, 0, v16
	v_add_u32_e32 v202, 0, v22
	s_waitcnt vmcnt(0)
	v_add_u32_e32 v205, 0, v17
	s_add_i32 s3, 0, 0x10000
	s_cmp_lg_u32 0, -1
	v_and_b32_e32 v182, 0xffffffe0, v48
	v_and_b32_e32 v68, 63, v64
	s_mov_b32 s68, s69
	s_mov_b32 s70, s69
	s_mov_b32 s71, s69
	s_mov_b32 s72, s69
	s_mov_b32 s73, s69
	s_mov_b32 s74, s69
	s_mov_b32 s75, s69
	s_mov_b32 s76, s69
	s_waitcnt vmcnt(0) lgkmcnt(0)
	ds_write_b128 v204, v[0:3]
	ds_write_b128 v205, v[4:7]
	ds_write_b128 v202, v[8:11] offset:32768
	ds_write_b128 v203, v[12:15] offset:32768
	v_bitop3_b32 v0, v180, v65, v66 bitop3:0xde
	v_add_u32_e32 v206, 0, v0
	s_waitcnt lgkmcnt(0)
	s_barrier
	ds_read_b128 v[0:3], v206 offset:32768
	ds_read_b128 v[4:7], v206 offset:40960
	s_waitcnt lgkmcnt(1)
	v_mfma_f32_32x32x16_bf16 v[16:31], v[0:3], v[118:121], 0
	v_or_b32_e32 v0, 32, v180
	v_bitop3_b32 v0, v0, v65, v66 bitop3:0xde
	v_add_u32_e32 v211, 0, v0
	v_and_b32_e32 v9, 0xc0, v49
	v_lshlrev_b32_e32 v8, 3, v68
	s_mov_b32 s77, s69
	s_mov_b32 s78, s69
	s_waitcnt lgkmcnt(0)
	v_mfma_f32_32x32x16_bf16 v[32:47], v[4:7], v[118:121], 0
	ds_read_b128 v[0:3], v211 offset:32768
	ds_read_b128 v[4:7], v211 offset:40960
	s_mov_b32 s79, s69
	s_mov_b32 s80, s69
	s_mov_b32 s81, s69
	s_mov_b32 s82, s69
	s_mov_b32 s83, s69
	s_mov_b32 s30, 4
	s_waitcnt lgkmcnt(1)
	v_mfma_f32_32x32x16_bf16 v[16:31], v[0:3], v[114:117], v[16:31]
	v_or_b32_e32 v0, 64, v180
	v_bitop3_b32 v0, v0, v65, v66 bitop3:0xde
	v_add_u32_e32 v210, 0, v0
	v_mov_b32_e32 v199, 0
	s_waitcnt lgkmcnt(0)
	v_mfma_f32_32x32x16_bf16 v[32:47], v[4:7], v[114:117], v[32:47]
	ds_read_b128 v[0:3], v210 offset:32768
	ds_read_b128 v[4:7], v210 offset:40960
	s_waitcnt lgkmcnt(1)
	v_mfma_f32_32x32x16_bf16 v[16:31], v[0:3], v[126:129], v[16:31]
	v_or_b32_e32 v0, 0x60, v180
	v_bitop3_b32 v0, v0, v65, v66 bitop3:0xde
	v_add_u32_e32 v209, 0, v0
	s_waitcnt lgkmcnt(0)
	v_mfma_f32_32x32x16_bf16 v[32:47], v[4:7], v[126:129], v[32:47]
	ds_read_b128 v[0:3], v209 offset:32768
	ds_read_b128 v[4:7], v209 offset:40960
	s_waitcnt lgkmcnt(1)
	v_mfma_f32_32x32x16_bf16 v[16:31], v[0:3], v[122:125], v[16:31]
	v_or_b32_e32 v0, 0x80, v180
	v_bitop3_b32 v0, v0, v65, v66 bitop3:0xde
	v_add_u32_e32 v208, 0, v0
	ds_read_b128 v[0:3], v208 offset:32768
	s_waitcnt lgkmcnt(1)
	v_mfma_f32_32x32x16_bf16 v[32:47], v[4:7], v[122:125], v[32:47]
	ds_read_b128 v[4:7], v208 offset:40960
	s_waitcnt lgkmcnt(1)
	v_mfma_f32_32x32x16_bf16 v[16:31], v[0:3], v[110:113], v[16:31]
	v_or_b32_e32 v1, 0xa0, v180
	v_bitop3_b32 v1, v1, v65, v66 bitop3:0xde
	v_and_b32_e32 v0, 0x3fffffc0, v64
	v_add_u32_e32 v207, 0, v1
	v_lshl_add_u32 v181, v0, 2, s3
	ds_read_b128 v[0:3], v207 offset:32768
	s_cselect_b32 s3, 0, 0
	s_add_u32 s20, s0, 0x4000
	s_addc_u32 s21, s1, 0
	s_add_u32 s24, s4, 0x4000
	s_waitcnt lgkmcnt(1)
; #define SWRITE(b, i) do { *(bf16x8*)((char*)V_lds + (b) * SHM_V + vst0) = sr_[i].vs0;          \
;     *(bf16x8*)((char*)V_lds + (b) * SHM_V + vst1) = sr_[i].vs1; int kc = sc * 2;               \
;     *(bf16x8*)((char*)K_lds + (b) * SHM_K + KSWZ(sr, kc)) = sr_[i].ks0;                       \
;     *(bf16x8*)((char*)K_lds + (b) * SHM_K + KSWZ(32 + sr, kc)) = sr_[i].ks1; } while (0)
; #define SWAIT() asm volatile("s_waitcnt vmcnt(4)" ::: "memory")
; __device__ __forceinline__ void partialSM(f32x16& p0, f32x16& p1, float& m_reg, float& mn, float& alpha) {
;   constexpr float C = SCALE * 1.4426950408889634f;
;   float pmax = p0[0];
; #pragma unroll
;   for (int r = 1; r < 16; ++r) pmax = fmaxf(pmax, p0[r]);
; #pragma unroll
;   for (int r = 0; r < 16; ++r) pmax = fmaxf(pmax, p1[r]);
;   { auto rr = __builtin_amdgcn_permlane32_swap(__float_as_uint(pmax), __float_as_uint(pmax), false, false);
;     pmax = fmaxf(__uint_as_float(rr[0]), __uint_as_float(rr[1])); }
;   if (__builtin_expect(__all(pmax - m_reg <= THR / SCALE), 1)) { mn = m_reg; alpha = 1.f; }
;   else { mn = fmaxf(m_reg, pmax); alpha = __builtin_amdgcn_exp2f((m_reg - mn) * C); m_reg = mn; }
;   float mnC = -mn * C;
; #pragma unroll
;   for (int r = 0; r < 16; ++r) p0[r] = fmaf(p0[r], C, mnC);
; #pragma unroll
;   for (int r = 0; r < 16; ++r) p1[r] = fmaf(p1[r], C, mnC);
; #pragma unroll
;   for (int r = 0; r < 16; ++r) p0[r] = __builtin_amdgcn_exp2f(p0[r]);
; }
; __device__ __forceinline__ void attn_body(const bf16_t* __restrict__ Qb, const bf16_t* __restrict__ Kh, const bf16_t* __restrict__ Vh,
;                                           bf16_t* __restrict__ Ob, const bf16_t* __restrict__ AGb, int seq, char* lds) {
;     ...
;   SLOAD(SO, KVBLK); if (2 < NT) SLOAD(SE, 2 * KVBLK);
;   SWAIT(); SWRITE(1, SO); __syncthreads();
	v_mfma_f32_32x32x16_bf16 v[32:47], v[4:7], v[110:113], v[32:47]
	ds_read_b128 v[4:7], v207 offset:40960
	s_addc_u32 s25, s5, 0
	s_add_u32 s4, s4, 0x8000
	s_addc_u32 s5, s5, 0
	s_add_u32 s0, s0, 0x8000
	s_addc_u32 s1, s1, 0
	v_lshl_add_u32 v183, v198, 2, v181
	s_waitcnt lgkmcnt(1)
	v_mfma_f32_32x32x16_bf16 v[16:31], v[0:3], v[106:109], v[16:31]
	v_lshl_add_u64 v[0:1], s[20:21], 0, v[96:97]
	v_lshl_add_u64 v[2:3], s[20:21], 0, v[184:185]
	global_load_dwordx4 v[48:51], v[0:1], off
	global_load_dwordx4 v[52:55], v[2:3], off
	v_lshl_add_u64 v[0:1], s[24:25], 0, v[96:97]
	v_lshl_add_u64 v[2:3], s[24:25], 0, v[184:185]
	global_load_dwordx4 v[56:59], v[0:1], off
	global_load_dwordx4 v[60:63], v[2:3], off
	v_or_b32_e32 v0, 0xc0, v180
	v_bitop3_b32 v0, v0, v65, v66 bitop3:0xde
	v_add_u32_e32 v213, 0, v0
	ds_read_b128 v[0:3], v213 offset:32768
	s_waitcnt lgkmcnt(0)
	v_mfma_f32_32x32x16_bf16 v[32:47], v[4:7], v[106:109], v[32:47]
	v_lshlrev_b32_e32 v5, 1, v64
	v_and_or_b32 v4, v8, 24, v9
	v_and_b32_e32 v5, 32, v5
	v_and_b32_e32 v6, 0x100, v8
	v_or3_b32 v69, v4, v5, v6
	ds_read_b128 v[4:7], v213 offset:40960
	v_add_u32_e32 v201, s3, v69
	v_mfma_f32_32x32x16_bf16 v[16:31], v[0:3], v[102:105], v[16:31]
	v_or_b32_e32 v0, 0xe0, v180
	v_bitop3_b32 v0, v0, v65, v66 bitop3:0xde
	v_add_u32_e32 v212, 0, v0
	ds_read_b128 v[0:3], v212 offset:32768
	ds_read_b128 v[64:67], v212 offset:40960
	s_waitcnt lgkmcnt(0)
	v_mfma_f32_32x32x16_bf16 v[32:47], v[4:7], v[102:105], v[32:47]
	v_mfma_f32_32x32x16_bf16 v[16:31], v[0:3], v[98:101], v[16:31]
	v_mov_b64_e32 v[0:1], s[68:69]
	v_mov_b64_e32 v[14:15], s[82:83]
	v_mov_b64_e32 v[2:3], s[70:71]
	v_mov_b64_e32 v[4:5], s[72:73]
	v_mov_b64_e32 v[6:7], s[74:75]
	v_mov_b64_e32 v[8:9], s[76:77]
	v_mov_b64_e32 v[10:11], s[78:79]
	v_mfma_f32_32x32x16_bf16 v[32:47], v[64:67], v[98:101], v[32:47]
	s_nop 3
	v_max_f32_e32 v64, v17, v17
	v_max_f32_e32 v65, v16, v16
	v_max_f32_e32 v64, v65, v64
	v_max3_f32 v64, v64, v18, v19
	v_max3_f32 v64, v64, v20, v21
	v_max3_f32 v64, v64, v22, v23
	v_max3_f32 v64, v64, v24, v25
	v_max3_f32 v64, v64, v26, v27
	v_max3_f32 v64, v64, v28, v29
	v_max3_f32 v64, v64, v30, v31
	v_max3_f32 v64, v64, v32, v33
	v_max3_f32 v64, v64, v34, v35
	v_max3_f32 v64, v64, v36, v37
	v_max3_f32 v70, v64, v38, v39
	v_lshl_add_u64 v[64:65], s[4:5], 0, v[184:185]
	v_lshl_add_u64 v[66:67], s[4:5], 0, v[96:97]
	global_load_dwordx4 v[142:145], v[64:65], off
	global_load_dwordx4 v[138:141], v[66:67], off
	v_lshl_add_u64 v[64:65], s[0:1], 0, v[184:185]
	v_lshl_add_u64 v[66:67], s[0:1], 0, v[96:97]
	global_load_dwordx4 v[134:137], v[64:65], off
	global_load_dwordx4 v[130:133], v[66:67], off
	v_max3_f32 v64, v70, v40, v41
	v_max3_f32 v64, v64, v42, v43
	v_max3_f32 v64, v64, v44, v45
	v_max3_f32 v64, v64, v46, v47
	v_mov_b32_e32 v65, v64
	s_nop 1
	v_permlane32_swap_b32_e32 v64, v65
	v_max_f32_e32 v65, v65, v65
	v_max_f32_e32 v64, v64, v64
	v_max_f32_e32 v64, v64, v65
	v_add_f32_e32 v65, 0x7149f2ca, v64
	v_cmp_ge_f32_e32 vcc, s62, v65
	s_cmp_eq_u64 vcc, exec
	s_waitcnt vmcnt(4)
	s_waitcnt vmcnt(0)
	ds_write_b128 v204, v[48:51] offset:16384
	ds_write_b128 v205, v[52:55] offset:16384
	ds_write_b128 v202, v[56:59] offset:49152
	ds_write_b128 v203, v[60:63] offset:49152
	v_max_f32_e32 v48, 0xf149f2ca, v64
	s_cselect_b64 vcc, -1, 0
	v_cndmask_b32_e32 v170, v48, v194, vcc
	v_sub_f32_e32 v49, 0xf149f2ca, v48
	v_mul_f32_e32 v48, 0xbe0293ee, v170
	v_fmamk_f32 v16, v16, 0x3e0293ee, v48
	v_exp_f32_e32 v163, v16
	v_fmamk_f32 v16, v17, 0x3e0293ee, v48
	v_exp_f32_e32 v177, v16
	v_fmamk_f32 v16, v18, 0x3e0293ee, v48
	v_exp_f32_e32 v164, v16
	v_fmamk_f32 v16, v19, 0x3e0293ee, v48
	v_exp_f32_e32 v186, v16
	v_fmamk_f32 v16, v20, 0x3e0293ee, v48
	v_exp_f32_e32 v176, v16
	v_fmamk_f32 v16, v21, 0x3e0293ee, v48
	v_exp_f32_e32 v187, v16
	v_fmamk_f32 v16, v22, 0x3e0293ee, v48
	v_exp_f32_e32 v165, v16
	v_fmamk_f32 v16, v23, 0x3e0293ee, v48
	v_exp_f32_e32 v175, v16
	v_fmamk_f32 v16, v24, 0x3e0293ee, v48
	v_mul_f32_e32 v49, 0x3e0293ee, v49
	v_exp_f32_e32 v166, v16
	v_fmamk_f32 v16, v25, 0x3e0293ee, v48
	v_exp_f32_e32 v49, v49
	v_exp_f32_e32 v173, v16
	v_fmamk_f32 v16, v26, 0x3e0293ee, v48
	v_exp_f32_e32 v167, v16
	v_fmamk_f32 v16, v27, 0x3e0293ee, v48
	v_exp_f32_e32 v174, v16
	v_fmamk_f32 v16, v28, 0x3e0293ee, v48
	v_exp_f32_e32 v168, v16
	v_fmamk_f32 v16, v29, 0x3e0293ee, v48
	v_pk_fma_f32 v[146:147], v[46:47], s[6:7], v[48:49] op_sel_hi:[1,0,0]
	v_pk_fma_f32 v[152:153], v[44:45], s[6:7], v[48:49] op_sel_hi:[1,0,0]
	v_pk_fma_f32 v[156:157], v[42:43], s[6:7], v[48:49] op_sel_hi:[1,0,0]
	v_pk_fma_f32 v[148:149], v[40:41], s[6:7], v[48:49] op_sel_hi:[1,0,0]
	v_pk_fma_f32 v[150:151], v[38:39], s[6:7], v[48:49] op_sel_hi:[1,0,0]
	v_pk_fma_f32 v[154:155], v[36:37], s[6:7], v[48:49] op_sel_hi:[1,0,0]
	v_pk_fma_f32 v[158:159], v[34:35], s[6:7], v[48:49] op_sel_hi:[1,0,0]
	v_pk_fma_f32 v[160:161], v[32:33], s[6:7], v[48:49] op_sel_hi:[1,0,0]
	v_exp_f32_e32 v171, v16
	v_fmamk_f32 v16, v30, 0x3e0293ee, v48
	v_fmac_f32_e32 v48, 0x3e0293ee, v31
	v_exp_f32_e32 v169, v16
	v_exp_f32_e32 v172, v48
	s_addk_i32 s3, 0x4000
	v_mov_b64_e32 v[12:13], s[80:81]
	v_cndmask_b32_e64 v214, v49, 1.0, vcc
	s_add_u32 s20, s54, s23
	v_mov_b64_e32 v[62:63], v[14:15]
	v_mov_b64_e32 v[46:47], v[14:15]
	v_mov_b64_e32 v[30:31], v[14:15]
	v_cmp_gt_u32_e64 s[4:5], 32, v68
	v_add_u32_e32 v200, s3, v69
	s_addc_u32 s21, s55, s22
	v_mov_b64_e32 v[60:61], v[12:13]
	v_mov_b64_e32 v[58:59], v[10:11]
	v_mov_b64_e32 v[56:57], v[8:9]
	v_mov_b64_e32 v[54:55], v[6:7]
	v_mov_b64_e32 v[52:53], v[4:5]
	v_mov_b64_e32 v[50:51], v[2:3]
	v_mov_b64_e32 v[48:49], v[0:1]
	v_mov_b64_e32 v[44:45], v[12:13]
	v_mov_b64_e32 v[42:43], v[10:11]
	v_mov_b64_e32 v[40:41], v[8:9]
	v_mov_b64_e32 v[38:39], v[6:7]
	v_mov_b64_e32 v[36:37], v[4:5]
	v_mov_b64_e32 v[34:35], v[2:3]
	v_mov_b64_e32 v[32:33], v[0:1]
	v_mov_b64_e32 v[28:29], v[12:13]
	v_mov_b64_e32 v[26:27], v[10:11]
	v_mov_b64_e32 v[24:25], v[8:9]
	v_mov_b64_e32 v[22:23], v[6:7]
	v_mov_b64_e32 v[20:21], v[4:5]
	v_mov_b64_e32 v[18:19], v[2:3]
	v_mov_b64_e32 v[16:17], v[0:1]
	s_waitcnt lgkmcnt(0)
	s_barrier
; #define SBAR() __builtin_amdgcn_sched_barrier(0)
; __device__ __forceinline__ void finishSM(f32x16& p0, f32x16& p1, float alpha, float& l_reg, bf16x8& pa0, bf16x8& pa1, bf16x8& pa2, bf16x8& pa3) {
; #pragma unroll
;   for (int r = 0; r < 16; ++r) p1[r] = __builtin_amdgcn_exp2f(p1[r]);
;   float ps = 0;
; #pragma unroll
;   for (int r = 0; r < 16; ++r) ps += p0[r];
; #pragma unroll
;   for (int r = 0; r < 16; ++r) ps += p1[r];
;   { auto rr = __builtin_amdgcn_permlane32_swap(__float_as_uint(ps), __float_as_uint(ps), false, false);
;     ps = __uint_as_float(rr[0]) + __uint_as_float(rr[1]); }
;   l_reg = l_reg * alpha + ps;
;     ...
;   PK4(p0, 0, pa0); PK4(p0, 8, pa1); PK4(p1, 0, pa2); PK4(p1, 8, pa3);
;     ...
; }
; __device__ __forceinline__ void qkt(f32x16& p0, f32x16& p1, const bf16_t* Ks, const bf16x8* qr, int r32, int hi) {
;   p0 = f32x16{}; p1 = f32x16{};
; #pragma unroll
;   for (int d0 = 0; d0 < 8; ++d0) { int cb = (d0 * 16 + hi * 8) * 2;
;     bf16x8 b0 = *reinterpret_cast<const bf16x8*>((const char*)Ks + KSWZ(r32, cb));
;     bf16x8 b1 = *reinterpret_cast<const bf16x8*>((const char*)Ks + KSWZ(32 + r32, cb));
;     p0 = __builtin_amdgcn_mfma_f32_32x32x16_bf16(b0, qr[d0], p0, 0, 0, 0);
;     p1 = __builtin_amdgcn_mfma_f32_32x32x16_bf16(b1, qr[d0], p1, 0, 0, 0); }
; __device__ __forceinline__ void attn_body(const bf16_t* __restrict__ Qb, const bf16_t* __restrict__ Kh, const bf16_t* __restrict__ Vh,
;                                           bf16_t* __restrict__ Ob, const bf16_t* __restrict__ AGb, int seq, char* lds) {
;     ...
;     SBAR(); qkt(pB0, pB1, (bf16_t*)((char*)K_lds + SHM_K), qr, r32, hi);
;     finishSM(pA0, pA1, alA, l_reg, pa0, pa1, pa2, pa3); SBAR();
;     SLOAD(SO, (j + 2) * KVBLK); SBAR();
;     pv_d0(o, vb0, pa0, pa1, pa2, pa3); partialSM(pB0, pB1, m_reg, mnB, alB);
.LBB0_199:
	ds_read_b128 v[64:67], v206 offset:49152
	ds_read_b128 v[68:71], v206 offset:57344
	ds_read_b128 v[216:219], v211 offset:49152
	ds_read_b128 v[220:223], v211 offset:57344
	v_add_f32_e32 v162, 0, v163
	v_add_f32_e32 v162, v177, v162
	s_waitcnt lgkmcnt(3)
	v_mfma_f32_32x32x16_bf16 v[80:95], v[64:67], v[118:121], 0
	v_add_f32_e32 v162, v164, v162
	v_add_f32_e32 v162, v186, v162
	v_add_f32_e32 v162, v176, v162
	v_add_f32_e32 v162, v187, v162
	v_add_f32_e32 v162, v165, v162
	v_add_f32_e32 v162, v175, v162
	v_add_f32_e32 v162, v166, v162
	s_waitcnt lgkmcnt(2)
	v_mfma_f32_32x32x16_bf16 v[64:79], v[68:71], v[118:121], 0
	v_add_f32_e32 v162, v173, v162
	v_add_f32_e32 v162, v167, v162
	v_add_f32_e32 v162, v174, v162
	v_exp_f32_e32 v160, v160
	v_add_f32_e32 v162, v168, v162
	v_exp_f32_e32 v161, v161
	v_add_f32_e32 v162, v171, v162
	s_waitcnt lgkmcnt(1)
	v_mfma_f32_32x32x16_bf16 v[80:95], v[216:219], v[114:117], v[80:95]
	v_exp_f32_e32 v158, v158
	v_add_f32_e32 v162, v169, v162
	v_exp_f32_e32 v159, v159
	v_add_f32_e32 v162, v172, v162
	v_exp_f32_e32 v154, v154
	v_add_f32_e32 v162, v160, v162
	v_exp_f32_e32 v155, v155
	s_waitcnt lgkmcnt(0)
	v_mfma_f32_32x32x16_bf16 v[64:79], v[220:223], v[114:117], v[64:79]
	ds_read_b128 v[216:219], v210 offset:49152
	ds_read_b128 v[220:223], v210 offset:57344
	v_add_f32_e32 v162, v161, v162
	v_exp_f32_e32 v150, v150
	v_add_f32_e32 v162, v158, v162
	v_exp_f32_e32 v151, v151
	v_add_f32_e32 v162, v159, v162
	v_exp_f32_e32 v148, v148
	s_waitcnt lgkmcnt(1)
	v_mfma_f32_32x32x16_bf16 v[80:95], v[216:219], v[126:129], v[80:95]
	v_add_f32_e32 v162, v154, v162
	v_exp_f32_e32 v149, v149
	v_add_f32_e32 v162, v155, v162
	v_exp_f32_e32 v156, v156
	v_add_f32_e32 v162, v150, v162
	v_exp_f32_e32 v157, v157
	v_add_f32_e32 v162, v151, v162
	s_waitcnt lgkmcnt(0)
	v_mfma_f32_32x32x16_bf16 v[64:79], v[220:223], v[126:129], v[64:79]
	ds_read_b128 v[216:219], v209 offset:49152
	ds_read_b128 v[220:223], v209 offset:57344
	v_exp_f32_e32 v152, v152
	v_add_f32_e32 v162, v148, v162
	v_exp_f32_e32 v153, v153
	v_add_f32_e32 v162, v149, v162
	v_exp_f32_e32 v146, v146
	v_add_f32_e32 v162, v156, v162
	s_waitcnt lgkmcnt(1)
	v_mfma_f32_32x32x16_bf16 v[80:95], v[216:219], v[122:125], v[80:95]
	v_exp_f32_e32 v147, v147
	v_add_f32_e32 v162, v157, v162
	v_add_f32_e32 v162, v152, v162
	v_add_f32_e32 v162, v153, v162
	v_add_f32_e32 v162, v146, v162
	v_add_f32_e32 v215, v147, v162
	s_waitcnt lgkmcnt(0)
	v_mfma_f32_32x32x16_bf16 v[64:79], v[220:223], v[122:125], v[64:79]
	ds_read_b128 v[216:219], v208 offset:49152
	ds_read_b128 v[220:223], v208 offset:57344
	s_waitcnt lgkmcnt(1)
	v_mfma_f32_32x32x16_bf16 v[80:95], v[216:219], v[110:113], v[80:95]
	s_waitcnt lgkmcnt(0)
	v_mfma_f32_32x32x16_bf16 v[64:79], v[220:223], v[110:113], v[64:79]
	ds_read_b128 v[216:219], v207 offset:49152
	ds_read_b128 v[220:223], v207 offset:57344
	s_waitcnt lgkmcnt(1)
	v_mfma_f32_32x32x16_bf16 v[80:95], v[216:219], v[106:109], v[80:95]
	s_waitcnt lgkmcnt(0)
	v_mfma_f32_32x32x16_bf16 v[64:79], v[220:223], v[106:109], v[64:79]
	ds_read_b128 v[216:219], v213 offset:49152
	ds_read_b128 v[220:223], v213 offset:57344
	s_waitcnt lgkmcnt(1)
	v_mfma_f32_32x32x16_bf16 v[80:95], v[216:219], v[102:105], v[80:95]
	s_waitcnt lgkmcnt(0)
	v_mfma_f32_32x32x16_bf16 v[64:79], v[220:223], v[102:105], v[64:79]
	ds_read_b128 v[216:219], v212 offset:49152
	ds_read_b128 v[220:223], v212 offset:57344
	v_cvt_pk_bf16_f32 v162, v163, v177
	v_cvt_pk_bf16_f32 v163, v164, v186
	v_cvt_pk_bf16_f32 v164, v176, v187
	v_cvt_pk_bf16_f32 v165, v165, v175
	v_cvt_pk_bf16_f32 v166, v166, v173
	v_cvt_pk_bf16_f32 v167, v167, v174
	s_waitcnt lgkmcnt(1)
	v_mfma_f32_32x32x16_bf16 v[80:95], v[216:219], v[98:101], v[80:95]
	v_mov_b32_e32 v216, v215
	s_nop 1
	v_permlane32_swap_b32_e32 v215, v216
	v_permlane32_swap_b32_e32 v162, v164
	v_cvt_pk_bf16_f32 v168, v168, v171
	v_cvt_pk_bf16_f32 v169, v169, v172
	s_waitcnt lgkmcnt(0)
	v_mfma_f32_32x32x16_bf16 v[64:79], v[220:223], v[98:101], v[64:79]
	ds_read_b64_tr_b16 v[222:223], v201 offset:0
	ds_read_b64_tr_b16 v[224:225], v201 offset:0x800
	ds_read_b64_tr_b16 v[226:227], v201 offset:0x1000
	ds_read_b64_tr_b16 v[228:229], v201 offset:0x1800
	ds_read_b64_tr_b16 v[230:231], v201 offset:0x2000
	ds_read_b64_tr_b16 v[232:233], v201 offset:0x2800
	ds_read_b64_tr_b16 v[234:235], v201 offset:0x3000
	ds_read_b64_tr_b16 v[236:237], v201 offset:0x3800
	v_cvt_pk_bf16_f32 v172, v160, v161
	v_cvt_pk_bf16_f32 v173, v158, v159
	v_cvt_pk_bf16_f32 v174, v154, v155
	v_cvt_pk_bf16_f32 v175, v150, v151
	v_cvt_pk_bf16_f32 v218, v148, v149
	v_cvt_pk_bf16_f32 v219, v156, v157
	v_cvt_pk_bf16_f32 v220, v152, v153
	v_cvt_pk_bf16_f32 v221, v146, v147
	v_permlane32_swap_b32_e32 v163, v165
	v_permlane32_swap_b32_e32 v166, v168
	v_permlane32_swap_b32_e32 v167, v169
	v_permlane32_swap_b32_e32 v172, v174
	v_permlane32_swap_b32_e32 v173, v175
	v_permlane32_swap_b32_e32 v218, v220
	v_permlane32_swap_b32_e32 v219, v221
	v_lshl_add_u64 v[188:189], s[20:21], 0, v[96:97]
	v_add_co_u32_e32 v146, vcc, s63, v188
	v_lshl_add_u64 v[186:187], s[20:21], 0, v[184:185]
	s_nop 0
	v_addc_co_u32_e32 v147, vcc, 0, v189, vcc
	v_add_co_u32_e32 v150, vcc, s63, v186
	s_nop 1
	v_addc_co_u32_e32 v151, vcc, 0, v187, vcc
	v_add_co_u32_e32 v154, vcc, s90, v188
	global_load_dwordx4 v[146:149], v[146:147], off
	s_nop 0
	global_load_dwordx4 v[150:153], v[150:151], off
	v_addc_co_u32_e32 v155, vcc, 0, v189, vcc
	v_add_co_u32_e32 v158, vcc, s90, v186
	s_nop 1
	v_addc_co_u32_e32 v159, vcc, 0, v187, vcc
	global_load_dwordx4 v[154:157], v[154:155], off
	s_nop 0
	global_load_dwordx4 v[158:161], v[158:159], off
	s_waitcnt lgkmcnt(0)
; #define SBAR() __builtin_amdgcn_sched_barrier(0)
; #define SWRITE(b, i) do { *(bf16x8*)((char*)V_lds + (b) * SHM_V + vst0) = sr_[i].vs0;          \
;     *(bf16x8*)((char*)V_lds + (b) * SHM_V + vst1) = sr_[i].vs1; int kc = sc * 2;               \
;     *(bf16x8*)((char*)K_lds + (b) * SHM_K + KSWZ(sr, kc)) = sr_[i].ks0;                       \
;     *(bf16x8*)((char*)K_lds + (b) * SHM_K + KSWZ(32 + sr, kc)) = sr_[i].ks1; } while (0)
; #define SWAIT() asm volatile("s_waitcnt vmcnt(4)" ::: "memory")
; #define RESC(a) do { if (__any((a) < 1.f)) { if (hi == 0) al_l[r32] = (a); asm volatile("s_waitcnt lgkmcnt(0)" ::: "memory"); \
;     _Pragma("unroll") for (int d = 0; d < 4; ++d) _Pragma("unroll") for (int r = 0; r < 16; ++r) o[d][r] *= al_l[crow(r, hi)]; } } while (0)
; template <int D0> __device__ __forceinline__ void pv_one(f32x16& od, int vb, bf16x8 pa0, bf16x8 pa1, bf16x8 pa2, bf16x8 pa3) {
;   const s16x4 l0 = tr_read<v_rd_off(D0, 0, 0)>(vb), h0 = tr_read<v_rd_off(D0, 0, 1)>(vb), l1 = tr_read<v_rd_off(D0, 1, 0)>(vb), h1 = tr_read<v_rd_off(D0, 1, 1)>(vb);
;   const s16x4 l2 = tr_read<v_rd_off(D0, 2, 0)>(vb), h2 = tr_read<v_rd_off(D0, 2, 1)>(vb), l3 = tr_read<v_rd_off(D0, 3, 0)>(vb), h3 = tr_read<v_rd_off(D0, 3, 1)>(vb);
;   asm volatile("s_waitcnt lgkmcnt(0)" ::: "memory"); SBAR();
;     ...
;   od = __builtin_amdgcn_mfma_f32_32x32x16_bf16(pa0, PK(l0, h0), od, 0, 0, 0);
;   od = __builtin_amdgcn_mfma_f32_32x32x16_bf16(pa1, PK(l1, h1), od, 0, 0, 0);
;   od = __builtin_amdgcn_mfma_f32_32x32x16_bf16(pa2, PK(l2, h2), od, 0, 0, 0);
;   od = __builtin_amdgcn_mfma_f32_32x32x16_bf16(pa3, PK(l3, h3), od, 0, 0, 0);
;     ...
; }
; __device__ __forceinline__ void pv_d0(f32x16* o, int vb, bf16x8 pa0, bf16x8 pa1, bf16x8 pa2, bf16x8 pa3) {
;   pv_one<0>(o[0], vb, pa0, pa1, pa2, pa3); pv_one<1>(o[1], vb, pa0, pa1, pa2, pa3); pv_one<2>(o[2], vb, pa0, pa1, pa2, pa3); pv_one<3>(o[3], vb, pa0, pa1, pa2, pa3);
; }
; __device__ __forceinline__ void attn_body(const bf16_t* __restrict__ Qb, const bf16_t* __restrict__ Kh, const bf16_t* __restrict__ Vh,
;                                           bf16_t* __restrict__ Ob, const bf16_t* __restrict__ AGb, int seq, char* lds) {
;     ...
;     pv_d0(o, vb0, pa0, pa1, pa2, pa3); partialSM(pB0, pB1, m_reg, mnB, alB);
;     __syncthreads(); SWAIT(); SWRITE(0, SE);
;     RESC(alB); __syncthreads();
	s_nop 0
	v_mfma_f32_32x32x16_bf16 v[0:15], v[162:165], v[222:225], v[0:15]
	ds_read_b64_tr_b16 v[222:223], v201 offset:0x200
	ds_read_b64_tr_b16 v[224:225], v201 offset:0xa00
	v_mfma_f32_32x32x16_bf16 v[0:15], v[166:169], v[226:229], v[0:15]
	ds_read_b64_tr_b16 v[226:227], v201 offset:0x1200
	ds_read_b64_tr_b16 v[228:229], v201 offset:0x1a00
	v_mfma_f32_32x32x16_bf16 v[0:15], v[172:175], v[230:233], v[0:15]
	ds_read_b64_tr_b16 v[230:231], v201 offset:0x2200
	ds_read_b64_tr_b16 v[232:233], v201 offset:0x2a00
	v_mfma_f32_32x32x16_bf16 v[0:15], v[218:221], v[234:237], v[0:15]
	ds_read_b64_tr_b16 v[234:235], v201 offset:0x3200
	ds_read_b64_tr_b16 v[236:237], v201 offset:0x3a00
	s_waitcnt lgkmcnt(0)
	v_mfma_f32_32x32x16_bf16 v[48:63], v[162:165], v[222:225], v[48:63]
	ds_read_b64_tr_b16 v[222:223], v201 offset:0x400
	ds_read_b64_tr_b16 v[224:225], v201 offset:0xc00
	v_mfma_f32_32x32x16_bf16 v[48:63], v[166:169], v[226:229], v[48:63]
	ds_read_b64_tr_b16 v[226:227], v201 offset:0x1400
	ds_read_b64_tr_b16 v[228:229], v201 offset:0x1c00
	v_mfma_f32_32x32x16_bf16 v[48:63], v[172:175], v[230:233], v[48:63]
	ds_read_b64_tr_b16 v[230:231], v201 offset:0x2400
	ds_read_b64_tr_b16 v[232:233], v201 offset:0x2c00
	v_mfma_f32_32x32x16_bf16 v[48:63], v[218:221], v[234:237], v[48:63]
	ds_read_b64_tr_b16 v[234:235], v201 offset:0x3400
	ds_read_b64_tr_b16 v[236:237], v201 offset:0x3c00
	s_waitcnt lgkmcnt(0)
	v_mfma_f32_32x32x16_bf16 v[32:47], v[162:165], v[222:225], v[32:47]
	ds_read_b64_tr_b16 v[222:223], v201 offset:0x600
	ds_read_b64_tr_b16 v[224:225], v201 offset:0xe00
	v_mfma_f32_32x32x16_bf16 v[32:47], v[166:169], v[226:229], v[32:47]
	ds_read_b64_tr_b16 v[226:227], v201 offset:0x1600
	ds_read_b64_tr_b16 v[228:229], v201 offset:0x1e00
	v_mfma_f32_32x32x16_bf16 v[32:47], v[172:175], v[230:233], v[32:47]
	ds_read_b64_tr_b16 v[230:231], v201 offset:0x2600
	ds_read_b64_tr_b16 v[232:233], v201 offset:0x2e00
	v_mfma_f32_32x32x16_bf16 v[32:47], v[218:221], v[234:237], v[32:47]
	ds_read_b64_tr_b16 v[234:235], v201 offset:0x3600
	ds_read_b64_tr_b16 v[236:237], v201 offset:0x3e00
	s_waitcnt lgkmcnt(0)
	v_mfma_f32_32x32x16_bf16 v[16:31], v[162:165], v[222:225], v[16:31]
	v_max_f32_e32 v162, v81, v81
	v_max_f32_e32 v163, v80, v80
	v_max_f32_e32 v162, v163, v162
	v_max3_f32 v162, v162, v82, v83
	v_max3_f32 v162, v162, v84, v85
	v_max3_f32 v162, v162, v86, v87
	v_max3_f32 v162, v162, v88, v89
	v_max3_f32 v162, v162, v90, v91
	v_max3_f32 v162, v162, v92, v93
	v_mfma_f32_32x32x16_bf16 v[16:31], v[166:169], v[226:229], v[16:31]
	v_max3_f32 v162, v162, v94, v95
	v_max3_f32 v162, v162, v64, v65
	v_max3_f32 v162, v162, v66, v67
	v_max3_f32 v162, v162, v68, v69
	v_max3_f32 v162, v162, v70, v71
	v_max3_f32 v162, v162, v72, v73
	v_max3_f32 v162, v162, v74, v75
	v_max3_f32 v162, v162, v76, v77
	v_mfma_f32_32x32x16_bf16 v[16:31], v[172:175], v[230:233], v[16:31]
	v_max3_f32 v162, v162, v78, v79
	v_mov_b32_e32 v163, v162
	s_nop 1
	v_permlane32_swap_b32_e32 v162, v163
	v_max_f32_e32 v163, v163, v163
	v_max_f32_e32 v162, v162, v162
	v_max_f32_e32 v162, v162, v163
	v_sub_f32_e32 v163, v162, v170
	v_cmp_ge_f32_e32 vcc, s62, v163
	v_max_f32_e32 v163, v170, v170
	v_max_f32_e32 v162, v163, v162
	v_mfma_f32_32x32x16_bf16 v[16:31], v[218:221], v[234:237], v[16:31]
	v_sub_f32_e32 v163, v170, v162
	v_mul_f32_e32 v163, 0x3e0293ee, v163
	v_exp_f32_e32 v163, v163
	s_cmp_eq_u64 vcc, exec
	s_cselect_b64 s[0:1], -1, 0
	s_waitcnt lgkmcnt(0)
	s_barrier
	s_waitcnt vmcnt(4)
	v_cndmask_b32_e64 v217, v163, 1.0, s[0:1]
	v_cmp_gt_f32_e32 vcc, 1.0, v217
	ds_write_b128 v204, v[130:133]
	ds_write_b128 v205, v[134:137]
	ds_write_b128 v202, v[138:141] offset:32768
	ds_write_b128 v203, v[142:145] offset:32768
	s_cbranch_vccz .LBB0_203
	s_and_saveexec_b64 s[22:23], s[4:5]
	ds_write_b32 v183, v217 offset:128
	s_or_b64 exec, exec, s[22:23]
	s_waitcnt lgkmcnt(0)
	v_add_u32_e32 v163, v181, v180
	ds_read_b128 v[164:167], v163 offset:224
	ds_read_b128 v[172:175], v163 offset:192
	ds_read_b128 v[218:221], v163 offset:160
	ds_read_b128 v[222:225], v163 offset:128
	s_waitcnt lgkmcnt(0)
	v_pk_mul_f32 v[12:13], v[12:13], v[164:165]
	v_pk_mul_f32 v[8:9], v[8:9], v[172:173]
	v_pk_mul_f32 v[4:5], v[4:5], v[218:219]
	v_pk_mul_f32 v[14:15], v[14:15], v[166:167]
	v_pk_mul_f32 v[10:11], v[10:11], v[174:175]
	v_pk_mul_f32 v[6:7], v[6:7], v[220:221]
	v_pk_mul_f32 v[2:3], v[2:3], v[224:225]
	v_pk_mul_f32 v[0:1], v[0:1], v[222:223]
	v_pk_mul_f32 v[60:61], v[60:61], v[164:165]
	v_pk_mul_f32 v[56:57], v[56:57], v[172:173]
	v_pk_mul_f32 v[52:53], v[52:53], v[218:219]
	v_pk_mul_f32 v[62:63], v[62:63], v[166:167]
	v_pk_mul_f32 v[58:59], v[58:59], v[174:175]
	v_pk_mul_f32 v[54:55], v[54:55], v[220:221]
	v_pk_mul_f32 v[50:51], v[50:51], v[224:225]
	v_pk_mul_f32 v[48:49], v[48:49], v[222:223]
	v_pk_mul_f32 v[44:45], v[44:45], v[164:165]
	v_pk_mul_f32 v[40:41], v[40:41], v[172:173]
	v_pk_mul_f32 v[36:37], v[36:37], v[218:219]
	v_pk_mul_f32 v[46:47], v[46:47], v[166:167]
	v_pk_mul_f32 v[42:43], v[42:43], v[174:175]
	v_pk_mul_f32 v[38:39], v[38:39], v[220:221]
	v_pk_mul_f32 v[34:35], v[34:35], v[224:225]
	v_pk_mul_f32 v[32:33], v[32:33], v[222:223]
	v_pk_mul_f32 v[28:29], v[28:29], v[164:165]
	v_pk_mul_f32 v[24:25], v[24:25], v[172:173]
	v_pk_mul_f32 v[20:21], v[20:21], v[218:219]
	v_pk_mul_f32 v[30:31], v[30:31], v[166:167]
	v_pk_mul_f32 v[26:27], v[26:27], v[174:175]
	v_pk_mul_f32 v[22:23], v[22:23], v[220:221]
	v_pk_mul_f32 v[18:19], v[18:19], v[224:225]
	v_pk_mul_f32 v[16:17], v[16:17], v[222:223]
; #define SBAR() __builtin_amdgcn_sched_barrier(0)
; __device__ __forceinline__ void partialSM(f32x16& p0, f32x16& p1, float& m_reg, float& mn, float& alpha) {
;   constexpr float C = SCALE * 1.4426950408889634f;
;   float pmax = p0[0];
; #pragma unroll
;   for (int r = 1; r < 16; ++r) pmax = fmaxf(pmax, p0[r]);
; #pragma unroll
;   for (int r = 0; r < 16; ++r) pmax = fmaxf(pmax, p1[r]);
;   { auto rr = __builtin_amdgcn_permlane32_swap(__float_as_uint(pmax), __float_as_uint(pmax), false, false);
;     pmax = fmaxf(__uint_as_float(rr[0]), __uint_as_float(rr[1])); }
;   if (__builtin_expect(__all(pmax - m_reg <= THR / SCALE), 1)) { mn = m_reg; alpha = 1.f; }
;   else { mn = fmaxf(m_reg, pmax); alpha = __builtin_amdgcn_exp2f((m_reg - mn) * C); m_reg = mn; }
;   float mnC = -mn * C;
; #pragma unroll
;   for (int r = 0; r < 16; ++r) p0[r] = fmaf(p0[r], C, mnC);
; #pragma unroll
;   for (int r = 0; r < 16; ++r) p1[r] = fmaf(p1[r], C, mnC);
; #pragma unroll
;   for (int r = 0; r < 16; ++r) p0[r] = __builtin_amdgcn_exp2f(p0[r]);
; }
; __device__ __forceinline__ void finishSM(f32x16& p0, f32x16& p1, float alpha, float& l_reg, bf16x8& pa0, bf16x8& pa1, bf16x8& pa2, bf16x8& pa3) {
; #pragma unroll
;   for (int r = 0; r < 16; ++r) p1[r] = __builtin_amdgcn_exp2f(p1[r]);
;   float ps = 0;
; #pragma unroll
;   for (int r = 0; r < 16; ++r) ps += p0[r];
; #pragma unroll
;   for (int r = 0; r < 16; ++r) ps += p1[r];
;   { auto rr = __builtin_amdgcn_permlane32_swap(__float_as_uint(ps), __float_as_uint(ps), false, false);
;     ps = __uint_as_float(rr[0]) + __uint_as_float(rr[1]); }
;   l_reg = l_reg * alpha + ps;
;     ...
;   PK4(p0, 0, pa0); PK4(p0, 8, pa1); PK4(p1, 0, pa2); PK4(p1, 8, pa3);
;     ...
; }
; __device__ __forceinline__ void attn_body(const bf16_t* __restrict__ Qb, const bf16_t* __restrict__ Kh, const bf16_t* __restrict__ Vh,
;                                           bf16_t* __restrict__ Ob, const bf16_t* __restrict__ AGb, int seq, char* lds) {
;     ...
;     SBAR(); qkt(pA0, pA1, K_lds, qr, r32, hi);
;     finishSM(pB0, pB1, alB, l_reg, pa0, pa1, pa2, pa3); SBAR();
;     if (j + 3 < NT) SLOAD(SE, (j + 3) * KVBLK); SBAR();
;     pv_d0(o, vb0 + (int)SHM_V, pa0, pa1, pa2, pa3); partialSM(pA0, pA1, m_reg, mnA, alA);
.LBB0_203:
	v_cndmask_b32_e64 v218, v162, v170, s[0:1]
	v_mul_f32_e32 v219, 0xbe0293ee, v218
	v_fmamk_f32 v80, v80, 0x3e0293ee, v219
	v_fmamk_f32 v81, v81, 0x3e0293ee, v219
	v_fmamk_f32 v82, v82, 0x3e0293ee, v219
	v_fmamk_f32 v83, v83, 0x3e0293ee, v219
	v_fmamk_f32 v84, v84, 0x3e0293ee, v219
	v_fmamk_f32 v85, v85, 0x3e0293ee, v219
	v_fmamk_f32 v86, v86, 0x3e0293ee, v219
	v_fmamk_f32 v87, v87, 0x3e0293ee, v219
	v_fmamk_f32 v88, v88, 0x3e0293ee, v219
	v_fmamk_f32 v89, v89, 0x3e0293ee, v219
	v_fmamk_f32 v90, v90, 0x3e0293ee, v219
	v_fmamk_f32 v91, v91, 0x3e0293ee, v219
	v_fmamk_f32 v92, v92, 0x3e0293ee, v219
	v_fmamk_f32 v93, v93, 0x3e0293ee, v219
	v_fmamk_f32 v94, v94, 0x3e0293ee, v219
	v_fmamk_f32 v95, v95, 0x3e0293ee, v219
	v_exp_f32_e32 v162, v80
	v_exp_f32_e32 v177, v81
	v_exp_f32_e32 v163, v82
	v_exp_f32_e32 v176, v83
	v_exp_f32_e32 v164, v84
	v_exp_f32_e32 v175, v85
	v_exp_f32_e32 v165, v86
	v_exp_f32_e32 v174, v87
	v_exp_f32_e32 v166, v88
	v_exp_f32_e32 v173, v89
	v_exp_f32_e32 v167, v90
	v_exp_f32_e32 v172, v91
	v_exp_f32_e32 v168, v92
	v_exp_f32_e32 v171, v93
	v_exp_f32_e32 v169, v94
	v_exp_f32_e32 v170, v95
	v_fmamk_f32 v228, v64, 0x3e0293ee, v219
	v_fmamk_f32 v229, v65, 0x3e0293ee, v219
	v_fmamk_f32 v230, v66, 0x3e0293ee, v219
	v_fmamk_f32 v231, v67, 0x3e0293ee, v219
	v_fmamk_f32 v232, v68, 0x3e0293ee, v219
	v_fmamk_f32 v221, v69, 0x3e0293ee, v219
	v_fmamk_f32 v222, v70, 0x3e0293ee, v219
	v_fmamk_f32 v223, v71, 0x3e0293ee, v219
	v_fmamk_f32 v224, v72, 0x3e0293ee, v219
	v_fmamk_f32 v225, v73, 0x3e0293ee, v219
	v_fmamk_f32 v226, v74, 0x3e0293ee, v219
	v_fmamk_f32 v227, v75, 0x3e0293ee, v219
	v_fmamk_f32 v220, v76, 0x3e0293ee, v219
	v_fmamk_f32 v233, v77, 0x3e0293ee, v219
	v_fmamk_f32 v234, v78, 0x3e0293ee, v219
	v_fmac_f32_e32 v219, 0x3e0293ee, v79
	s_waitcnt lgkmcnt(0)
	s_barrier
	ds_read_b128 v[64:67], v206 offset:32768
	ds_read_b128 v[68:71], v206 offset:40960
	ds_read_b128 v[236:239], v211 offset:32768
	ds_read_b128 v[240:243], v211 offset:40960
	v_exp_f32_e32 v228, v228
	v_exp_f32_e32 v229, v229
	s_waitcnt lgkmcnt(0)
	v_mfma_f32_32x32x16_bf16 v[80:95], v[64:67], v[118:121], 0
	v_exp_f32_e32 v230, v230
	v_exp_f32_e32 v231, v231
	v_exp_f32_e32 v232, v232
	v_exp_f32_e32 v221, v221
	v_exp_f32_e32 v222, v222
	v_exp_f32_e32 v223, v223
	v_exp_f32_e32 v224, v224
	v_mfma_f32_32x32x16_bf16 v[64:79], v[68:71], v[118:121], 0
	v_exp_f32_e32 v225, v225
	v_exp_f32_e32 v226, v226
	v_exp_f32_e32 v227, v227
	v_exp_f32_e32 v235, v220
	v_exp_f32_e32 v233, v233
	v_exp_f32_e32 v234, v234
	v_mfma_f32_32x32x16_bf16 v[80:95], v[236:239], v[114:117], v[80:95]
	v_mfma_f32_32x32x16_bf16 v[64:79], v[240:243], v[114:117], v[64:79]
	ds_read_b128 v[236:239], v210 offset:32768
	ds_read_b128 v[240:243], v210 offset:40960
	s_waitcnt lgkmcnt(0)
	v_mfma_f32_32x32x16_bf16 v[80:95], v[236:239], v[126:129], v[80:95]
	v_mfma_f32_32x32x16_bf16 v[64:79], v[240:243], v[126:129], v[64:79]
	ds_read_b128 v[236:239], v209 offset:32768
	ds_read_b128 v[240:243], v209 offset:40960
	s_waitcnt lgkmcnt(0)
	v_mfma_f32_32x32x16_bf16 v[80:95], v[236:239], v[122:125], v[80:95]
	v_mfma_f32_32x32x16_bf16 v[64:79], v[240:243], v[122:125], v[64:79]
	ds_read_b128 v[236:239], v208 offset:32768
	ds_read_b128 v[240:243], v208 offset:40960
	s_waitcnt lgkmcnt(0)
	v_mfma_f32_32x32x16_bf16 v[80:95], v[236:239], v[110:113], v[80:95]
	v_mfma_f32_32x32x16_bf16 v[64:79], v[240:243], v[110:113], v[64:79]
	ds_read_b128 v[236:239], v207 offset:32768
	ds_read_b128 v[240:243], v207 offset:40960
	s_waitcnt lgkmcnt(0)
	v_mfma_f32_32x32x16_bf16 v[80:95], v[236:239], v[106:109], v[80:95]
	v_mfma_f32_32x32x16_bf16 v[64:79], v[240:243], v[106:109], v[64:79]
	ds_read_b128 v[236:239], v213 offset:32768
	ds_read_b128 v[240:243], v213 offset:40960
	s_waitcnt lgkmcnt(0)
	v_mfma_f32_32x32x16_bf16 v[80:95], v[236:239], v[102:105], v[80:95]
	v_mfma_f32_32x32x16_bf16 v[64:79], v[240:243], v[102:105], v[64:79]
	ds_read_b128 v[236:239], v212 offset:32768
	ds_read_b128 v[240:243], v212 offset:40960
	s_waitcnt lgkmcnt(0)
	v_mfma_f32_32x32x16_bf16 v[80:95], v[236:239], v[98:101], v[80:95]
	v_exp_f32_e32 v236, v219
	v_add_f32_e32 v219, 0, v162
	v_add_f32_e32 v219, v177, v219
	v_add_f32_e32 v219, v163, v219
	v_add_f32_e32 v219, v176, v219
	v_add_f32_e32 v219, v164, v219
	v_add_f32_e32 v219, v175, v219
	v_add_f32_e32 v219, v165, v219
	v_add_f32_e32 v219, v174, v219
	v_add_f32_e32 v219, v166, v219
	v_add_f32_e32 v219, v173, v219
	v_add_f32_e32 v219, v167, v219
	v_add_f32_e32 v219, v172, v219
	v_add_f32_e32 v219, v168, v219
	v_add_f32_e32 v219, v171, v219
	v_add_f32_e32 v219, v169, v219
	v_add_f32_e32 v219, v170, v219
	v_add_f32_e32 v219, v228, v219
	v_add_f32_e32 v219, v229, v219
	v_add_f32_e32 v219, v230, v219
	v_add_f32_e32 v219, v231, v219
	v_add_f32_e32 v219, v232, v219
	v_add_f32_e32 v219, v221, v219
	v_add_f32_e32 v219, v222, v219
	v_add_f32_e32 v219, v223, v219
	v_add_f32_e32 v219, v224, v219
	v_add_f32_e32 v219, v225, v219
	v_mfma_f32_32x32x16_bf16 v[64:79], v[240:243], v[98:101], v[64:79]
	v_add_f32_e32 v219, v226, v219
	v_add_f32_e32 v219, v227, v219
	v_add_f32_e32 v219, v235, v219
	v_add_f32_e32 v219, v233, v219
	v_add_f32_e32 v219, v234, v219
	v_add_f32_e32 v219, v236, v219
	v_mov_b32_e32 v220, v219
	v_cvt_pk_bf16_f32 v162, v162, v177
	v_cvt_pk_bf16_f32 v163, v163, v176
	v_cvt_pk_bf16_f32 v164, v164, v175
	v_cvt_pk_bf16_f32 v165, v165, v174
	v_cvt_pk_bf16_f32 v166, v166, v173
	v_cvt_pk_bf16_f32 v167, v167, v172
	v_cvt_pk_bf16_f32 v168, v168, v171
	v_cvt_pk_bf16_f32 v169, v169, v170
	v_cvt_pk_bf16_f32 v170, v228, v229
	v_cvt_pk_bf16_f32 v171, v230, v231
	v_cvt_pk_bf16_f32 v172, v232, v221
	v_cvt_pk_bf16_f32 v173, v222, v223
	v_cvt_pk_bf16_f32 v174, v224, v225
	v_cvt_pk_bf16_f32 v175, v226, v227
	v_cvt_pk_bf16_f32 v176, v235, v233
	v_cvt_pk_bf16_f32 v177, v234, v236
	ds_read_b64_tr_b16 v[222:223], v200 offset:0x1000
	ds_read_b64_tr_b16 v[224:225], v200 offset:0x1800
	ds_read_b64_tr_b16 v[226:227], v200 offset:0x2000
	ds_read_b64_tr_b16 v[228:229], v200 offset:0x2800
	ds_read_b64_tr_b16 v[230:231], v200 offset:0x3000
	ds_read_b64_tr_b16 v[232:233], v200 offset:0x3800
	s_nop 1
	v_permlane32_swap_b32_e32 v219, v220
	v_permlane32_swap_b32_e32 v162, v164
	v_permlane32_swap_b32_e32 v163, v165
	v_permlane32_swap_b32_e32 v166, v168
	v_permlane32_swap_b32_e32 v167, v169
	v_permlane32_swap_b32_e32 v170, v172
	v_permlane32_swap_b32_e32 v171, v173
	v_permlane32_swap_b32_e32 v174, v176
	v_permlane32_swap_b32_e32 v175, v177
	s_cmp_ge_u32 s30, s29
	s_cselect_b64 s[22:23], -1, 0
	s_and_b64 vcc, exec, s[22:23]
	s_cbranch_vccnz .LBB0_205
; #define SBAR() __builtin_amdgcn_sched_barrier(0)
; #define SWRITE(b, i) do { *(bf16x8*)((char*)V_lds + (b) * SHM_V + vst0) = sr_[i].vs0;          \
;     *(bf16x8*)((char*)V_lds + (b) * SHM_V + vst1) = sr_[i].vs1; int kc = sc * 2;               \
;     *(bf16x8*)((char*)K_lds + (b) * SHM_K + KSWZ(sr, kc)) = sr_[i].ks0;                       \
;     *(bf16x8*)((char*)K_lds + (b) * SHM_K + KSWZ(32 + sr, kc)) = sr_[i].ks1; } while (0)
; #define SWAIT() asm volatile("s_waitcnt vmcnt(4)" ::: "memory")
; template <int D0> __device__ __forceinline__ void pv_one(f32x16& od, int vb, bf16x8 pa0, bf16x8 pa1, bf16x8 pa2, bf16x8 pa3) {
;   const s16x4 l0 = tr_read<v_rd_off(D0, 0, 0)>(vb), h0 = tr_read<v_rd_off(D0, 0, 1)>(vb), l1 = tr_read<v_rd_off(D0, 1, 0)>(vb), h1 = tr_read<v_rd_off(D0, 1, 1)>(vb);
;   const s16x4 l2 = tr_read<v_rd_off(D0, 2, 0)>(vb), h2 = tr_read<v_rd_off(D0, 2, 1)>(vb), l3 = tr_read<v_rd_off(D0, 3, 0)>(vb), h3 = tr_read<v_rd_off(D0, 3, 1)>(vb);
;   asm volatile("s_waitcnt lgkmcnt(0)" ::: "memory"); SBAR();
;     ...
;   od = __builtin_amdgcn_mfma_f32_32x32x16_bf16(pa0, PK(l0, h0), od, 0, 0, 0);
;   od = __builtin_amdgcn_mfma_f32_32x32x16_bf16(pa1, PK(l1, h1), od, 0, 0, 0);
;   od = __builtin_amdgcn_mfma_f32_32x32x16_bf16(pa2, PK(l2, h2), od, 0, 0, 0);
;   od = __builtin_amdgcn_mfma_f32_32x32x16_bf16(pa3, PK(l3, h3), od, 0, 0, 0);
;     ...
; }
; __device__ __forceinline__ void pv_d0(f32x16* o, int vb, bf16x8 pa0, bf16x8 pa1, bf16x8 pa2, bf16x8 pa3) {
;   pv_one<0>(o[0], vb, pa0, pa1, pa2, pa3); pv_one<1>(o[1], vb, pa0, pa1, pa2, pa3); pv_one<2>(o[2], vb, pa0, pa1, pa2, pa3); pv_one<3>(o[3], vb, pa0, pa1, pa2, pa3);
; }
; __device__ __forceinline__ void attn_body(const bf16_t* __restrict__ Qb, const bf16_t* __restrict__ Kh, const bf16_t* __restrict__ Vh,
;                                           bf16_t* __restrict__ Ob, const bf16_t* __restrict__ AGb, int seq, char* lds) {
;     ...
;     if (j + 3 < NT) SLOAD(SE, (j + 3) * KVBLK); SBAR();
;     pv_d0(o, vb0 + (int)SHM_V, pa0, pa1, pa2, pa3); partialSM(pA0, pA1, m_reg, mnA, alA);
;     __syncthreads(); SWAIT(); SWRITE(1, SO);
;     RESC(alA); __syncthreads();
	v_add_co_u32_e32 v130, vcc, 0x48888000, v188
	s_nop 1
	v_addc_co_u32_e32 v131, vcc, 0, v189, vcc
	v_add_co_u32_e32 v134, vcc, 0x48888000, v186
	s_nop 1
	v_addc_co_u32_e32 v135, vcc, 0, v187, vcc
	v_add_co_u32_e32 v138, vcc, 0x48048000, v188
	global_load_dwordx4 v[130:133], v[130:131], off
	s_nop 0
	global_load_dwordx4 v[134:137], v[134:135], off
	v_addc_co_u32_e32 v139, vcc, 0, v189, vcc
	v_add_co_u32_e32 v142, vcc, 0x48048000, v186
	s_nop 1
	v_addc_co_u32_e32 v143, vcc, 0, v187, vcc
	global_load_dwordx4 v[138:141], v[138:139], off
	s_nop 0
	global_load_dwordx4 v[142:145], v[142:143], off
.LBB0_205:
	ds_read_b64_tr_b16 v[186:187], v200 offset:0
	ds_read_b64_tr_b16 v[188:189], v200 offset:0x800
	s_waitcnt lgkmcnt(0)
	s_nop 0
	v_mfma_f32_32x32x16_bf16 v[0:15], v[162:165], v[186:189], v[0:15]
	ds_read_b64_tr_b16 v[186:187], v200 offset:0x200
	ds_read_b64_tr_b16 v[188:189], v200 offset:0xa00
	v_mfma_f32_32x32x16_bf16 v[0:15], v[166:169], v[222:225], v[0:15]
	ds_read_b64_tr_b16 v[222:223], v200 offset:0x1200
	ds_read_b64_tr_b16 v[224:225], v200 offset:0x1a00
	v_mfma_f32_32x32x16_bf16 v[0:15], v[170:173], v[226:229], v[0:15]
	ds_read_b64_tr_b16 v[226:227], v200 offset:0x2200
	ds_read_b64_tr_b16 v[228:229], v200 offset:0x2a00
	v_mfma_f32_32x32x16_bf16 v[0:15], v[174:177], v[230:233], v[0:15]
	ds_read_b64_tr_b16 v[230:231], v200 offset:0x3200
	ds_read_b64_tr_b16 v[232:233], v200 offset:0x3a00
	s_waitcnt lgkmcnt(0)
	v_mfma_f32_32x32x16_bf16 v[48:63], v[162:165], v[186:189], v[48:63]
	ds_read_b64_tr_b16 v[186:187], v200 offset:0x400
	ds_read_b64_tr_b16 v[188:189], v200 offset:0xc00
	v_mfma_f32_32x32x16_bf16 v[48:63], v[166:169], v[222:225], v[48:63]
	ds_read_b64_tr_b16 v[222:223], v200 offset:0x1400
	ds_read_b64_tr_b16 v[224:225], v200 offset:0x1c00
	v_mfma_f32_32x32x16_bf16 v[48:63], v[170:173], v[226:229], v[48:63]
	ds_read_b64_tr_b16 v[226:227], v200 offset:0x2400
	ds_read_b64_tr_b16 v[228:229], v200 offset:0x2c00
	v_mfma_f32_32x32x16_bf16 v[48:63], v[174:177], v[230:233], v[48:63]
	ds_read_b64_tr_b16 v[230:231], v200 offset:0x3400
	ds_read_b64_tr_b16 v[232:233], v200 offset:0x3c00
	s_waitcnt lgkmcnt(0)
	v_mfma_f32_32x32x16_bf16 v[32:47], v[162:165], v[186:189], v[32:47]
	ds_read_b64_tr_b16 v[186:187], v200 offset:0x600
	ds_read_b64_tr_b16 v[188:189], v200 offset:0xe00
	v_mfma_f32_32x32x16_bf16 v[32:47], v[166:169], v[222:225], v[32:47]
	ds_read_b64_tr_b16 v[222:223], v200 offset:0x1600
	ds_read_b64_tr_b16 v[224:225], v200 offset:0x1e00
	v_mfma_f32_32x32x16_bf16 v[32:47], v[170:173], v[226:229], v[32:47]
	ds_read_b64_tr_b16 v[226:227], v200 offset:0x2600
	ds_read_b64_tr_b16 v[228:229], v200 offset:0x2e00
	v_mfma_f32_32x32x16_bf16 v[32:47], v[174:177], v[230:233], v[32:47]
	ds_read_b64_tr_b16 v[230:231], v200 offset:0x3600
	ds_read_b64_tr_b16 v[232:233], v200 offset:0x3e00
	s_waitcnt lgkmcnt(0)
	v_mfma_f32_32x32x16_bf16 v[16:31], v[162:165], v[186:189], v[16:31]
	v_max_f32_e32 v162, v81, v81
	v_max_f32_e32 v163, v80, v80
	v_max_f32_e32 v162, v163, v162
	v_max3_f32 v162, v162, v82, v83
	v_max3_f32 v162, v162, v84, v85
	v_max3_f32 v162, v162, v86, v87
	v_max3_f32 v162, v162, v88, v89
	v_max3_f32 v162, v162, v90, v91
	v_max3_f32 v162, v162, v92, v93
	v_mfma_f32_32x32x16_bf16 v[16:31], v[166:169], v[222:225], v[16:31]
	v_max3_f32 v162, v162, v94, v95
	v_max3_f32 v162, v162, v64, v65
	v_max3_f32 v162, v162, v66, v67
	v_max3_f32 v162, v162, v68, v69
	v_max3_f32 v162, v162, v70, v71
	v_max3_f32 v162, v162, v72, v73
	v_max3_f32 v162, v162, v74, v75
	v_max3_f32 v162, v162, v76, v77
	v_mfma_f32_32x32x16_bf16 v[16:31], v[170:173], v[226:229], v[16:31]
	v_max3_f32 v162, v162, v78, v79
	v_mov_b32_e32 v163, v162
	s_nop 1
	v_permlane32_swap_b32_e32 v162, v163
	v_max_f32_e32 v163, v163, v163
	v_max_f32_e32 v162, v162, v162
	v_max_f32_e32 v162, v162, v163
	v_sub_f32_e32 v163, v162, v218
	v_cmp_ge_f32_e32 vcc, s62, v163
	v_max_f32_e32 v163, v218, v218
	v_max_f32_e32 v163, v163, v162
	v_mfma_f32_32x32x16_bf16 v[16:31], v[174:177], v[230:233], v[16:31]
	v_sub_f32_e32 v162, v218, v163
	v_mul_f32_e32 v162, 0x3e0293ee, v162
	v_exp_f32_e32 v162, v162
	s_cmp_eq_u64 vcc, exec
	s_cselect_b64 s[0:1], -1, 0
	s_waitcnt lgkmcnt(0)
	s_barrier
	s_waitcnt vmcnt(4)
	v_cndmask_b32_e64 v162, v162, 1.0, s[0:1]
	v_cmp_gt_f32_e32 vcc, 1.0, v162
	s_waitcnt vmcnt(0)
	ds_write_b128 v204, v[146:149] offset:16384
	ds_write_b128 v205, v[150:153] offset:16384
	ds_write_b128 v202, v[154:157] offset:49152
	ds_write_b128 v203, v[158:161] offset:49152
	s_cbranch_vccz .LBB0_209
	s_and_saveexec_b64 s[24:25], s[4:5]
	ds_write_b32 v183, v162 offset:128
	s_or_b64 exec, exec, s[24:25]
	s_waitcnt lgkmcnt(0)
	v_add_u32_e32 v158, v181, v180
	ds_read_b128 v[146:149], v158 offset:224
	ds_read_b128 v[150:153], v158 offset:192
	ds_read_b128 v[154:157], v158 offset:160
	ds_read_b128 v[158:161], v158 offset:128
	s_waitcnt lgkmcnt(3)
	v_pk_mul_f32 v[12:13], v[12:13], v[146:147]
	s_waitcnt lgkmcnt(2)
	v_pk_mul_f32 v[8:9], v[8:9], v[150:151]
	s_waitcnt lgkmcnt(1)
	v_pk_mul_f32 v[4:5], v[4:5], v[154:155]
	v_pk_mul_f32 v[14:15], v[14:15], v[148:149]
	v_pk_mul_f32 v[10:11], v[10:11], v[152:153]
	v_pk_mul_f32 v[6:7], v[6:7], v[156:157]
	s_waitcnt lgkmcnt(0)
	v_pk_mul_f32 v[2:3], v[2:3], v[160:161]
	v_pk_mul_f32 v[0:1], v[0:1], v[158:159]
	v_pk_mul_f32 v[60:61], v[60:61], v[146:147]
	v_pk_mul_f32 v[56:57], v[56:57], v[150:151]
	v_pk_mul_f32 v[52:53], v[52:53], v[154:155]
	v_pk_mul_f32 v[62:63], v[62:63], v[148:149]
	v_pk_mul_f32 v[58:59], v[58:59], v[152:153]
	v_pk_mul_f32 v[54:55], v[54:55], v[156:157]
	v_pk_mul_f32 v[50:51], v[50:51], v[160:161]
	v_pk_mul_f32 v[48:49], v[48:49], v[158:159]
	v_pk_mul_f32 v[44:45], v[44:45], v[146:147]
	v_pk_mul_f32 v[40:41], v[40:41], v[150:151]
	v_pk_mul_f32 v[36:37], v[36:37], v[154:155]
	v_pk_mul_f32 v[46:47], v[46:47], v[148:149]
	v_pk_mul_f32 v[42:43], v[42:43], v[152:153]
	v_pk_mul_f32 v[38:39], v[38:39], v[156:157]
	v_pk_mul_f32 v[34:35], v[34:35], v[160:161]
	v_pk_mul_f32 v[32:33], v[32:33], v[158:159]
	v_pk_mul_f32 v[28:29], v[28:29], v[146:147]
	v_pk_mul_f32 v[24:25], v[24:25], v[150:151]
	v_pk_mul_f32 v[20:21], v[20:21], v[154:155]
	v_pk_mul_f32 v[30:31], v[30:31], v[148:149]
	v_pk_mul_f32 v[26:27], v[26:27], v[152:153]
	v_pk_mul_f32 v[22:23], v[22:23], v[156:157]
	v_pk_mul_f32 v[18:19], v[18:19], v[160:161]
	v_pk_mul_f32 v[16:17], v[16:17], v[158:159]

; #define LAS __attribute__((address_space(3)))
; __device__ __forceinline__ unsigned xb_xcc_id() { return (unsigned)__builtin_amdgcn_s_getreg((3 << 11) | 20) & 0xFu; }
; __global__ void __launch_bounds__(NTHREADS, 2) mega_fwd(Params p0) {
;     ...
;             case 5: gemm_phase(L, G_DFTC, l, p.ws); break;
;     ...
;             __syncthreads();
;             if (sync) { XcdBarrier xb; xb.bar = (unsigned*)(p.ws + WS_BAR); xb.x = xb_xcc_id(); xb.st = (volatile LAS unsigned*)((LAS unsigned char*)lds + LDS_STAGE); xcd_barrier(xb); }
.LBB0_408:
	s_cmp_eq_u32 s46, 5
	s_cselect_b64 s[4:5], 0, s[4:5]
	s_andn2_b64 vcc, exec, s[4:5]
	v_readlane_b32 s48, v245, 32
	s_waitcnt vmcnt(0) lgkmcnt(0)
	s_barrier
	s_cbranch_vccz .LBB0_409
	s_getpc_b64 s[98:99]
